# K-loop: issue each segment's two LDS-DMA loads before its ds_reads (earlier global issue)
# baseline (speedup 1.0000x reference)
.LBB0_744:
	s_add_i32 s44, s4, 2
	s_add_u32 s8, s6, 0x80
	s_addc_u32 s5, s7, 0
	s_add_i32 s45, 0, 0x10000
	v_add_u32_e32 v140, s45, v234
	s_cmp_eq_u32 s27, s4
	s_cselect_b32 s4, s90, s8
	s_cselect_b32 s5, s91, s5
	s_cselect_b32 s9, s93, s43
	s_cselect_b32 s8, s92, s42
	v_lshl_add_u64 v[214:215], s[6:7], 0, v[206:207]
	s_add_i32 m0, s74, 0xc000
	s_nop 0
	global_load_lds_dwordx4 v[214:215], off
	v_lshl_add_u64 v[214:215], s[6:7], 0, v[208:209]
	s_add_i32 m0, s74, 0xe000
	s_nop 0
	global_load_lds_dwordx4 v[214:215], off
	ds_read_b128 v[128:131], v140
	ds_read_b128 v[132:135], v140 offset:1024
	ds_read_b128 v[136:139], v140 offset:2048
	ds_read_b128 v[140:143], v140 offset:3072
	ds_read_b128 v[144:147], v235
	ds_read_b128 v[148:151], v235 offset:1024
	ds_read_b128 v[152:155], v235 offset:2048
	ds_read_b128 v[156:159], v235 offset:3072
	ds_read_b128 v[160:163], v235 offset:4096
	ds_read_b128 v[164:167], v235 offset:5120
	ds_read_b128 v[168:171], v235 offset:6144
	ds_read_b128 v[210:213], v235 offset:7168
	s_waitcnt lgkmcnt(8)
	s_barrier
	s_waitcnt lgkmcnt(0)
	s_waitcnt lgkmcnt(0)
	v_mfma_f32_16x16x32_bf16 v[108:111], v[128:131], v[144:147], v[108:111]
	v_mfma_f32_16x16x32_bf16 v[104:107], v[136:139], v[144:147], v[104:107]
	v_mfma_f32_16x16x32_bf16 v[92:95], v[128:131], v[152:155], v[92:95]
	v_mfma_f32_16x16x32_bf16 v[80:83], v[136:139], v[152:155], v[80:83]
	v_mfma_f32_16x16x32_bf16 v[68:71], v[128:131], v[160:163], v[68:71]
	v_mfma_f32_16x16x32_bf16 v[56:59], v[136:139], v[160:163], v[56:59]
	v_mfma_f32_16x16x32_bf16 v[44:47], v[128:131], v[168:171], v[44:47]
	v_mfma_f32_16x16x32_bf16 v[32:35], v[136:139], v[168:171], v[32:35]
	v_mfma_f32_16x16x32_bf16 v[108:111], v[132:135], v[148:151], v[108:111]
	v_mfma_f32_16x16x32_bf16 v[104:107], v[140:143], v[148:151], v[104:107]
	v_mfma_f32_16x16x32_bf16 v[92:95], v[132:135], v[156:159], v[92:95]
	v_mfma_f32_16x16x32_bf16 v[80:83], v[140:143], v[156:159], v[80:83]
	v_mfma_f32_16x16x32_bf16 v[68:71], v[132:135], v[164:167], v[68:71]
	v_mfma_f32_16x16x32_bf16 v[56:59], v[140:143], v[164:167], v[56:59]
	v_mfma_f32_16x16x32_bf16 v[44:47], v[132:135], v[210:213], v[44:47]
	v_mfma_f32_16x16x32_bf16 v[32:35], v[140:143], v[210:213], v[32:35]
	s_barrier
	s_add_i32 s45, s45, s97
	v_add_u32_e32 v172, s3, v234
	v_lshl_add_u64 v[244:245], s[8:9], 0, v[184:185]
	s_mov_b32 m0, s45
	s_nop 0
	global_load_lds_dwordx4 v[244:245], off
	v_lshl_add_u64 v[246:247], s[8:9], 0, v[188:189]
	s_add_i32 m0, s45, 0x2000
	s_nop 0
	global_load_lds_dwordx4 v[246:247], off
	ds_read_b128 v[214:217], v172
	ds_read_b128 v[218:221], v172 offset:1024
	ds_read_b128 v[236:239], v172 offset:2048
	ds_read_b128 v[240:243], v172 offset:3072
	s_barrier
	s_waitcnt lgkmcnt(0)
	s_waitcnt lgkmcnt(0)
	v_mfma_f32_16x16x32_bf16 v[124:127], v[214:217], v[144:147], v[124:127]
	v_mfma_f32_16x16x32_bf16 v[120:123], v[236:239], v[144:147], v[120:123]
	v_mfma_f32_16x16x32_bf16 v[116:119], v[214:217], v[152:155], v[116:119]
	v_mfma_f32_16x16x32_bf16 v[112:115], v[236:239], v[152:155], v[112:115]
	v_mfma_f32_16x16x32_bf16 v[100:103], v[214:217], v[160:163], v[100:103]
	v_mfma_f32_16x16x32_bf16 v[96:99], v[236:239], v[160:163], v[96:99]
	v_mfma_f32_16x16x32_bf16 v[76:79], v[214:217], v[168:171], v[76:79]
	v_mfma_f32_16x16x32_bf16 v[72:75], v[236:239], v[168:171], v[72:75]
	v_mfma_f32_16x16x32_bf16 v[124:127], v[218:221], v[148:151], v[124:127]
	v_mfma_f32_16x16x32_bf16 v[120:123], v[240:243], v[148:151], v[120:123]
	v_mfma_f32_16x16x32_bf16 v[116:119], v[218:221], v[156:159], v[116:119]
	v_mfma_f32_16x16x32_bf16 v[112:115], v[240:243], v[156:159], v[112:115]
	v_mfma_f32_16x16x32_bf16 v[100:103], v[218:221], v[164:167], v[100:103]
	v_mfma_f32_16x16x32_bf16 v[96:99], v[240:243], v[164:167], v[96:99]
	v_mfma_f32_16x16x32_bf16 v[76:79], v[218:221], v[210:213], v[76:79]
	v_mfma_f32_16x16x32_bf16 v[72:75], v[240:243], v[210:213], v[72:75]
	s_mov_b32 m0, s74
	v_lshl_add_u64 v[248:249], s[4:5], 0, v[182:183]
	s_barrier
	global_load_lds_dwordx4 v[248:249], off
	v_lshl_add_u64 v[250:251], s[4:5], 0, v[186:187]
	s_mov_b32 m0, s56
	s_nop 0
	global_load_lds_dwordx4 v[250:251], off
	ds_read_b128 v[144:147], v235 offset:16384
	ds_read_b128 v[148:151], v235 offset:17408
	ds_read_b128 v[152:155], v235 offset:18432
	ds_read_b128 v[156:159], v235 offset:19456
	ds_read_b128 v[160:163], v235 offset:20480
	ds_read_b128 v[164:167], v235 offset:21504
	ds_read_b128 v[168:171], v235 offset:22528
	ds_read_b128 v[210:213], v235 offset:23552
	s_barrier
	s_waitcnt lgkmcnt(0)
	s_waitcnt lgkmcnt(0)
	v_mfma_f32_16x16x32_bf16 v[52:55], v[128:131], v[144:147], v[52:55]
	v_mfma_f32_16x16x32_bf16 v[48:51], v[136:139], v[144:147], v[48:51]
	v_mfma_f32_16x16x32_bf16 v[28:31], v[128:131], v[152:155], v[28:31]
	v_mfma_f32_16x16x32_bf16 v[24:27], v[136:139], v[152:155], v[24:27]
	v_mfma_f32_16x16x32_bf16 v[12:15], v[128:131], v[160:163], v[12:15]
	v_mfma_f32_16x16x32_bf16 v[8:11], v[136:139], v[160:163], v[8:11]
	v_mfma_f32_16x16x32_bf16 v[4:7], v[128:131], v[168:171], v[4:7]
	v_mfma_f32_16x16x32_bf16 v[0:3], v[136:139], v[168:171], v[0:3]
	v_mfma_f32_16x16x32_bf16 v[52:55], v[132:135], v[148:151], v[52:55]
	v_mfma_f32_16x16x32_bf16 v[48:51], v[140:143], v[148:151], v[48:51]
	v_mfma_f32_16x16x32_bf16 v[28:31], v[132:135], v[156:159], v[28:31]
	v_mfma_f32_16x16x32_bf16 v[24:27], v[140:143], v[156:159], v[24:27]
	v_mfma_f32_16x16x32_bf16 v[12:15], v[132:135], v[164:167], v[12:15]
	v_mfma_f32_16x16x32_bf16 v[8:11], v[140:143], v[164:167], v[8:11]
	v_mfma_f32_16x16x32_bf16 v[4:7], v[132:135], v[210:213], v[4:7]
	v_mfma_f32_16x16x32_bf16 v[0:3], v[140:143], v[210:213], v[0:3]
	s_barrier
	s_add_u32 s8, s8, s78
	s_addc_u32 s9, s9, 0
	s_add_i32 s45, s3, s97
	v_lshl_add_u64 v[252:253], s[8:9], 0, v[184:185]
	s_mov_b32 m0, s45
	v_lshl_add_u64 v[230:231], s[8:9], 0, v[188:189]
	global_load_lds_dwordx4 v[252:253], off
	s_add_i32 m0, s45, 0x2000
	s_nop 0
	global_load_lds_dwordx4 v[230:231], off
	s_waitcnt vmcnt(6)
	s_barrier
	v_mfma_f32_16x16x32_bf16 v[88:91], v[214:217], v[144:147], v[88:91]
	v_mfma_f32_16x16x32_bf16 v[84:87], v[236:239], v[144:147], v[84:87]
	v_mfma_f32_16x16x32_bf16 v[64:67], v[214:217], v[152:155], v[64:67]
	v_mfma_f32_16x16x32_bf16 v[60:63], v[236:239], v[152:155], v[60:63]
	v_mfma_f32_16x16x32_bf16 v[40:43], v[214:217], v[160:163], v[40:43]
	v_mfma_f32_16x16x32_bf16 v[36:39], v[236:239], v[160:163], v[36:39]
	v_mfma_f32_16x16x32_bf16 v[20:23], v[214:217], v[168:171], v[20:23]
	v_mfma_f32_16x16x32_bf16 v[16:19], v[236:239], v[168:171], v[16:19]
	v_mfma_f32_16x16x32_bf16 v[88:91], v[218:221], v[148:151], v[88:91]
	v_mfma_f32_16x16x32_bf16 v[84:87], v[240:243], v[148:151], v[84:87]
	v_mfma_f32_16x16x32_bf16 v[64:67], v[218:221], v[156:159], v[64:67]
	v_mfma_f32_16x16x32_bf16 v[60:63], v[240:243], v[156:159], v[60:63]
	v_mfma_f32_16x16x32_bf16 v[40:43], v[218:221], v[164:167], v[40:43]
	v_mfma_f32_16x16x32_bf16 v[36:39], v[240:243], v[164:167], v[36:39]
	v_mfma_f32_16x16x32_bf16 v[20:23], v[218:221], v[210:213], v[20:23]
	v_mfma_f32_16x16x32_bf16 v[16:19], v[240:243], v[210:213], v[16:19]
	s_add_i32 s8, 0, 0x18000
	v_add_u32_e32 v140, s8, v234
	s_barrier
	s_add_u32 s4, s4, s60
	s_addc_u32 s5, s5, 0
	s_mov_b32 m0, s57
	v_lshl_add_u64 v[214:215], s[4:5], 0, v[182:183]
	global_load_lds_dwordx4 v[214:215], off
	v_lshl_add_u64 v[214:215], s[4:5], 0, v[186:187]
	s_mov_b32 m0, s68
	s_nop 0
	global_load_lds_dwordx4 v[214:215], off
	ds_read_b128 v[128:131], v140
	ds_read_b128 v[132:135], v140 offset:1024
	ds_read_b128 v[136:139], v140 offset:2048
	ds_read_b128 v[140:143], v140 offset:3072
	ds_read_b128 v[144:147], v235 offset:32768
	ds_read_b128 v[148:151], v235 offset:33792
	ds_read_b128 v[152:155], v235 offset:34816
	ds_read_b128 v[156:159], v235 offset:35840
	ds_read_b128 v[160:163], v235 offset:36864
	ds_read_b128 v[164:167], v235 offset:37888
	ds_read_b128 v[168:171], v235 offset:38912
	ds_read_b128 v[210:213], v235 offset:39936
	s_waitcnt lgkmcnt(8)
	s_barrier
	s_waitcnt lgkmcnt(0)
	s_waitcnt lgkmcnt(0)
	v_mfma_f32_16x16x32_bf16 v[108:111], v[128:131], v[144:147], v[108:111]
	v_mfma_f32_16x16x32_bf16 v[104:107], v[136:139], v[144:147], v[104:107]
	v_mfma_f32_16x16x32_bf16 v[92:95], v[128:131], v[152:155], v[92:95]
	v_mfma_f32_16x16x32_bf16 v[80:83], v[136:139], v[152:155], v[80:83]
	v_mfma_f32_16x16x32_bf16 v[68:71], v[128:131], v[160:163], v[68:71]
	v_mfma_f32_16x16x32_bf16 v[56:59], v[136:139], v[160:163], v[56:59]
	v_mfma_f32_16x16x32_bf16 v[44:47], v[128:131], v[168:171], v[44:47]
	v_mfma_f32_16x16x32_bf16 v[32:35], v[136:139], v[168:171], v[32:35]
	v_mfma_f32_16x16x32_bf16 v[108:111], v[132:135], v[148:151], v[108:111]
	v_mfma_f32_16x16x32_bf16 v[104:107], v[140:143], v[148:151], v[104:107]
	v_mfma_f32_16x16x32_bf16 v[92:95], v[132:135], v[156:159], v[92:95]
	v_mfma_f32_16x16x32_bf16 v[80:83], v[140:143], v[156:159], v[80:83]
	v_mfma_f32_16x16x32_bf16 v[68:71], v[132:135], v[164:167], v[68:71]
	v_mfma_f32_16x16x32_bf16 v[56:59], v[140:143], v[164:167], v[56:59]
	v_mfma_f32_16x16x32_bf16 v[44:47], v[132:135], v[210:213], v[44:47]
	v_mfma_f32_16x16x32_bf16 v[32:35], v[140:143], v[210:213], v[32:35]
	s_barrier
	s_add_i32 s4, 0, 0x1c000
	s_add_i32 s5, s8, s97
	v_add_u32_e32 v172, s4, v234
	v_lshl_add_u64 v[244:245], v[244:245], 0, s[54:55]
	s_mov_b32 m0, s5
	s_nop 0
	global_load_lds_dwordx4 v[244:245], off
	v_lshl_add_u64 v[244:245], v[246:247], 0, s[54:55]
	s_add_i32 m0, s5, 0x2000
	s_nop 0
	global_load_lds_dwordx4 v[244:245], off
	ds_read_b128 v[214:217], v172
	ds_read_b128 v[218:221], v172 offset:1024
	ds_read_b128 v[236:239], v172 offset:2048
	ds_read_b128 v[240:243], v172 offset:3072
	s_barrier
	s_waitcnt lgkmcnt(0)
	s_waitcnt lgkmcnt(0)
	v_mfma_f32_16x16x32_bf16 v[124:127], v[214:217], v[144:147], v[124:127]
	v_mfma_f32_16x16x32_bf16 v[120:123], v[236:239], v[144:147], v[120:123]
	v_mfma_f32_16x16x32_bf16 v[116:119], v[214:217], v[152:155], v[116:119]
	v_mfma_f32_16x16x32_bf16 v[112:115], v[236:239], v[152:155], v[112:115]
	v_mfma_f32_16x16x32_bf16 v[100:103], v[214:217], v[160:163], v[100:103]
	v_mfma_f32_16x16x32_bf16 v[96:99], v[236:239], v[160:163], v[96:99]
	v_mfma_f32_16x16x32_bf16 v[76:79], v[214:217], v[168:171], v[76:79]
	v_mfma_f32_16x16x32_bf16 v[72:75], v[236:239], v[168:171], v[72:75]
	v_mfma_f32_16x16x32_bf16 v[124:127], v[218:221], v[148:151], v[124:127]
	v_mfma_f32_16x16x32_bf16 v[120:123], v[240:243], v[148:151], v[120:123]
	v_mfma_f32_16x16x32_bf16 v[116:119], v[218:221], v[156:159], v[116:119]
	v_mfma_f32_16x16x32_bf16 v[112:115], v[240:243], v[156:159], v[112:115]
	v_mfma_f32_16x16x32_bf16 v[100:103], v[218:221], v[164:167], v[100:103]
	v_mfma_f32_16x16x32_bf16 v[96:99], v[240:243], v[164:167], v[96:99]
	v_mfma_f32_16x16x32_bf16 v[76:79], v[218:221], v[210:213], v[76:79]
	v_mfma_f32_16x16x32_bf16 v[72:75], v[240:243], v[210:213], v[72:75]
	s_mov_b32 m0, s69
	v_lshl_add_u64 v[244:245], v[248:249], 0, s[54:55]
	s_barrier
	global_load_lds_dwordx4 v[244:245], off
	v_lshl_add_u64 v[244:245], v[250:251], 0, s[54:55]
	s_mov_b32 m0, s26
	s_nop 0
	global_load_lds_dwordx4 v[244:245], off
	ds_read_b128 v[144:147], v235 offset:49152
	ds_read_b128 v[148:151], v235 offset:50176
	ds_read_b128 v[152:155], v235 offset:51200
	ds_read_b128 v[156:159], v235 offset:52224
	ds_read_b128 v[160:163], v235 offset:53248
	ds_read_b128 v[164:167], v235 offset:54272
	ds_read_b128 v[168:171], v235 offset:55296
	ds_read_b128 v[210:213], v235 offset:56320
	s_barrier
	s_waitcnt lgkmcnt(0)
	s_waitcnt lgkmcnt(0)
	v_mfma_f32_16x16x32_bf16 v[52:55], v[128:131], v[144:147], v[52:55]
	v_mfma_f32_16x16x32_bf16 v[48:51], v[136:139], v[144:147], v[48:51]
	v_mfma_f32_16x16x32_bf16 v[28:31], v[128:131], v[152:155], v[28:31]
	v_mfma_f32_16x16x32_bf16 v[24:27], v[136:139], v[152:155], v[24:27]
	v_mfma_f32_16x16x32_bf16 v[12:15], v[128:131], v[160:163], v[12:15]
	v_mfma_f32_16x16x32_bf16 v[8:11], v[136:139], v[160:163], v[8:11]
	v_mfma_f32_16x16x32_bf16 v[4:7], v[128:131], v[168:171], v[4:7]
	v_mfma_f32_16x16x32_bf16 v[0:3], v[136:139], v[168:171], v[0:3]
	v_mfma_f32_16x16x32_bf16 v[52:55], v[132:135], v[148:151], v[52:55]
	v_mfma_f32_16x16x32_bf16 v[48:51], v[140:143], v[148:151], v[48:51]
	v_mfma_f32_16x16x32_bf16 v[28:31], v[132:135], v[156:159], v[28:31]
	v_mfma_f32_16x16x32_bf16 v[24:27], v[140:143], v[156:159], v[24:27]
	v_mfma_f32_16x16x32_bf16 v[12:15], v[132:135], v[164:167], v[12:15]
	v_mfma_f32_16x16x32_bf16 v[8:11], v[140:143], v[164:167], v[8:11]
	v_mfma_f32_16x16x32_bf16 v[4:7], v[132:135], v[210:213], v[4:7]
	v_mfma_f32_16x16x32_bf16 v[0:3], v[140:143], v[210:213], v[0:3]
	s_barrier
	s_add_i32 s4, s4, s97
	v_lshl_add_u64 v[128:129], v[252:253], 0, s[54:55]
	s_mov_b32 m0, s4
	s_nop 0
	global_load_lds_dwordx4 v[128:129], off
	v_lshl_add_u64 v[128:129], v[230:231], 0, s[54:55]
	s_add_i32 m0, s4, 0x2000
	s_nop 0
	global_load_lds_dwordx4 v[128:129], off
	s_waitcnt vmcnt(6)
	s_barrier
	v_mfma_f32_16x16x32_bf16 v[88:91], v[214:217], v[144:147], v[88:91]
	v_mfma_f32_16x16x32_bf16 v[84:87], v[236:239], v[144:147], v[84:87]
	v_mfma_f32_16x16x32_bf16 v[64:67], v[214:217], v[152:155], v[64:67]
	v_mfma_f32_16x16x32_bf16 v[60:63], v[236:239], v[152:155], v[60:63]
	v_mfma_f32_16x16x32_bf16 v[40:43], v[214:217], v[160:163], v[40:43]
	v_mfma_f32_16x16x32_bf16 v[36:39], v[236:239], v[160:163], v[36:39]
	v_mfma_f32_16x16x32_bf16 v[20:23], v[214:217], v[168:171], v[20:23]
	v_mfma_f32_16x16x32_bf16 v[16:19], v[236:239], v[168:171], v[16:19]
	v_mfma_f32_16x16x32_bf16 v[88:91], v[218:221], v[148:151], v[88:91]
	v_mfma_f32_16x16x32_bf16 v[84:87], v[240:243], v[148:151], v[84:87]
	v_mfma_f32_16x16x32_bf16 v[64:67], v[218:221], v[156:159], v[64:67]
	v_mfma_f32_16x16x32_bf16 v[60:63], v[240:243], v[156:159], v[60:63]
	v_mfma_f32_16x16x32_bf16 v[40:43], v[218:221], v[164:167], v[40:43]
	v_mfma_f32_16x16x32_bf16 v[36:39], v[240:243], v[164:167], v[36:39]
	v_mfma_f32_16x16x32_bf16 v[20:23], v[218:221], v[210:213], v[20:23]
	v_mfma_f32_16x16x32_bf16 v[16:19], v[240:243], v[210:213], v[16:19]
	s_add_u32 s6, s6, 0x100
	s_addc_u32 s7, s7, 0
	s_add_u32 s42, s42, 0x100
	s_addc_u32 s43, s43, 0
	s_cmp_ge_u32 s44, s73
	s_mov_b32 s4, s44
	s_barrier
	s_cbranch_scc0 .LBB0_744
	s_lshl_b32 s52, s30, 8
	s_cmp_lt_i32 s96, 2
	s_mov_b64 s[4:5], -1
	s_cbranch_scc1 .LBB0_898
	s_cmp_gt_i32 s96, 2
	s_cbranch_scc0 .LBB0_895
	s_add_i32 s30, s52, s82
	v_or_b32_e32 v210, s30, v179
	s_and_b32 s4, s10, -4
	s_cmp_lg_u32 s4, 4
	s_movk_i32 s4, 0x2000
	s_movk_i32 s6, 0x1fff
	v_or_b32_e32 v212, 16, v210
	v_cmp_gt_i32_e32 vcc, s4, v210
	v_cmp_lt_i32_e64 s[42:43], s6, v210
	s_mov_b64 s[4:5], -1
	v_ashrrev_i32_e32 v211, 31, v210
	s_movk_i32 s53, 0x1fff
	v_cmp_lt_i32_e64 s[46:47], s6, v212
	s_cbranch_scc0 .LBB0_829
	v_lshlrev_b32_e32 v128, 6, v212
	s_movk_i32 s4, 0x2000
	v_and_b32_e32 v128, 0x3f7c0, v128
	v_cmp_gt_i32_e64 s[44:45], s4, v212
	v_lshlrev_b32_e32 v219, 6, v210
	v_and_b32_e32 v144, 0x3f3c0, v219
	v_cndmask_b32_e64 v128, v225, v128, s[44:45]
	v_lshlrev_b32_e32 v172, 2, v128
	v_cndmask_b32_e32 v144, v225, v144, vcc
	v_lshl_add_u64 v[132:133], v[196:197], 0, v[172:173]
	v_lshl_add_u64 v[140:141], v[198:199], 0, v[172:173]
	v_lshlrev_b32_e32 v172, 2, v144
	v_lshl_add_u64 v[144:145], v[198:199], 0, v[172:173]
	global_load_dwordx4 v[128:131], v[132:133], off offset:16
	global_load_dwordx4 v[136:139], v[132:133], off
	s_nop 0
	global_load_dwordx4 v[132:135], v[140:141], off offset:16
	s_nop 0
	global_load_dwordx4 v[140:143], v[140:141], off
	s_nop 0
	global_load_dwordx4 v[156:159], v[144:145], off offset:16
	global_load_dwordx4 v[152:155], v[144:145], off
	v_lshl_add_u64 v[144:145], v[196:197], 0, v[172:173]
	global_load_dwordx4 v[160:163], v[144:145], off offset:16
	global_load_dwordx4 v[164:167], v[144:145], off
	s_cmp_gt_i32 s10, 3
	s_cselect_b64 s[4:5], -1, 0
	s_lshl_b32 s6, s10, 1
	s_add_i32 s7, s6, -16
	s_cmp_lt_i32 s10, 4
	s_cselect_b32 s6, s6, s7
	v_readlane_b32 s7, v255, 50
	s_or_b32 s6, s6, s7
	s_lshl_b32 s94, s6, 7
	s_ashr_i32 s95, s94, 31
	s_lshl_b64 s[6:7], s[94:95], 1
	v_lshl_add_u64 v[214:215], v[200:201], 0, s[6:7]
	s_waitcnt vmcnt(0)
	v_pk_mul_f32 v[144:145], v[126:127], v[154:155]
	v_pk_mul_f32 v[148:149], v[124:125], v[152:153]
	v_pk_fma_f32 v[146:147], v[110:111], v[166:167], v[144:145] neg_lo:[0,0,1] neg_hi:[0,0,1]
	v_pk_fma_f32 v[144:145], v[108:109], v[164:165], v[148:149] neg_lo:[0,0,1] neg_hi:[0,0,1]
	v_pk_mul_f32 v[148:149], v[122:123], v[158:159]
	v_pk_mul_f32 v[168:169], v[120:121], v[156:157]
	v_pk_fma_f32 v[150:151], v[106:107], v[162:163], v[148:149] neg_lo:[0,0,1] neg_hi:[0,0,1]
	v_pk_fma_f32 v[148:149], v[104:105], v[160:161], v[168:169] neg_lo:[0,0,1] neg_hi:[0,0,1]
	v_pk_mul_f32 v[166:167], v[126:127], v[166:167]
	v_pk_mul_f32 v[164:165], v[124:125], v[164:165]
	v_pk_mul_f32 v[162:163], v[122:123], v[162:163]
	v_pk_mul_f32 v[160:161], v[120:121], v[160:161]
	v_pk_fma_f32 v[154:155], v[110:111], v[154:155], v[166:167]
	v_pk_fma_f32 v[152:153], v[108:109], v[152:153], v[164:165]
	v_pk_fma_f32 v[158:159], v[106:107], v[158:159], v[162:163]
	v_pk_fma_f32 v[156:157], v[104:105], v[156:157], v[160:161]
	v_cvt_pk_bf16_f32 v160, v144, v145
	v_cvt_pk_bf16_f32 v161, v146, v147
	v_cvt_pk_bf16_f32 v162, v148, v149
	v_cvt_pk_bf16_f32 v163, v150, v151
	v_cvt_pk_bf16_f32 v164, v152, v153
	v_cvt_pk_bf16_f32 v165, v154, v155
	v_cvt_pk_bf16_f32 v166, v156, v157
	v_cvt_pk_bf16_f32 v167, v158, v159
	s_mov_b64 s[8:9], -1
	s_and_b64 vcc, exec, s[4:5]
	s_cbranch_vccz .LBB0_750
	s_movk_i32 s8, 0x1800
	v_mad_i64_i32 v[168:169], s[8:9], v210, s8, v[214:215]
	global_store_dwordx4 v[168:169], v[160:163], off
	global_store_dwordx4 v[168:169], v[164:167], off offset:128
	s_mov_b64 s[8:9], 0
